# s27 + dma_saddr: 20 K-loop LDS-DMA loads use the SGPR-base form (no per-load 64-bit VALU address add)
# speedup vs baseline: 1.0095x; 1.0095x over previous
.LBB0_124:
	ds_read_b128 v[160:163], v202
	ds_read_b128 v[164:167], v202 offset:1024
	ds_read_b128 v[168:171], v202 offset:2048
	ds_read_b128 v[172:175], v202 offset:3072
	ds_read_b128 v[208:211], v203
	ds_read_b128 v[212:215], v203 offset:1024
	ds_read_b128 v[218:221], v203 offset:2048
	ds_read_b128 v[222:225], v203 offset:3072
	s_add_i32 s15, s14, 2
	s_add_u32 s10, s12, s6
	s_addc_u32 s11, s13, s7
	s_cmpk_eq_i32 s6, 0x700
	s_cselect_b32 s16, s85, s9
	s_cselect_b32 s17, s84, s8
	s_cselect_b32 s86, 0, s15
	s_cselect_b32 s11, s57, s11
	s_cselect_b32 s10, s56, s10
	v_lshl_add_u64 v[192:193], v[156:157], 0, s[6:7]
	s_add_i32 m0, s39, 0xc000
	ds_read_b128 v[226:229], v204
	ds_read_b128 v[230:233], v204 offset:1024
	ds_read_b128 v[234:237], v204 offset:2048
	ds_read_b128 v[238:241], v204 offset:3072
	ds_read_b128 v[242:245], v204 offset:4096
	ds_read_b128 v[246:249], v204 offset:5120
	ds_read_b128 v[250:253], v204 offset:6144
	ds_read_b128 v[186:189], v204 offset:7168
	global_load_lds_dwordx4 v[192:193], off
	v_lshl_add_u64 v[192:193], v[158:159], 0, s[6:7]
	s_add_i32 m0, s39, 0xe000
	s_nop 0
	global_load_lds_dwordx4 v[192:193], off
	s_waitcnt vmcnt(8)
	s_waitcnt lgkmcnt(0)
	s_barrier
	s_setprio 1
	v_mfma_f32_16x16x32_bf16 v[124:127], v[160:163], v[226:229], v[124:127]
	v_mfma_f32_16x16x32_bf16 v[120:123], v[168:171], v[226:229], v[120:123]
	v_mfma_f32_16x16x32_bf16 v[108:111], v[160:163], v[234:237], v[108:111]
	v_mfma_f32_16x16x32_bf16 v[104:107], v[168:171], v[234:237], v[104:107]
	v_mfma_f32_16x16x32_bf16 v[92:95], v[160:163], v[242:245], v[92:95]
	v_mfma_f32_16x16x32_bf16 v[88:91], v[168:171], v[242:245], v[88:91]
	v_mfma_f32_16x16x32_bf16 v[76:79], v[160:163], v[250:253], v[76:79]
	v_mfma_f32_16x16x32_bf16 v[72:75], v[168:171], v[250:253], v[72:75]
	v_mfma_f32_16x16x32_bf16 v[124:127], v[164:167], v[230:233], v[124:127]
	v_mfma_f32_16x16x32_bf16 v[120:123], v[172:175], v[230:233], v[120:123]
	v_mfma_f32_16x16x32_bf16 v[108:111], v[164:167], v[238:241], v[108:111]
	v_mfma_f32_16x16x32_bf16 v[104:107], v[172:175], v[238:241], v[104:107]
	v_mfma_f32_16x16x32_bf16 v[92:95], v[164:167], v[246:249], v[92:95]
	v_mfma_f32_16x16x32_bf16 v[88:91], v[172:175], v[246:249], v[88:91]
	v_mfma_f32_16x16x32_bf16 v[76:79], v[164:167], v[186:189], v[76:79]
	v_mfma_f32_16x16x32_bf16 v[72:75], v[172:175], v[186:189], v[72:75]
	v_mfma_f32_16x16x32_bf16 v[116:119], v[208:211], v[226:229], v[116:119]
	v_mfma_f32_16x16x32_bf16 v[112:115], v[218:221], v[226:229], v[112:115]
	v_mfma_f32_16x16x32_bf16 v[100:103], v[208:211], v[234:237], v[100:103]
	v_mfma_f32_16x16x32_bf16 v[96:99], v[218:221], v[234:237], v[96:99]
	v_mfma_f32_16x16x32_bf16 v[84:87], v[208:211], v[242:245], v[84:87]
	v_mfma_f32_16x16x32_bf16 v[80:83], v[218:221], v[242:245], v[80:83]
	v_mfma_f32_16x16x32_bf16 v[68:71], v[208:211], v[250:253], v[68:71]
	v_mfma_f32_16x16x32_bf16 v[64:67], v[218:221], v[250:253], v[64:67]
	v_mfma_f32_16x16x32_bf16 v[116:119], v[212:215], v[230:233], v[116:119]
	v_mfma_f32_16x16x32_bf16 v[112:115], v[222:225], v[230:233], v[112:115]
	v_mfma_f32_16x16x32_bf16 v[100:103], v[212:215], v[238:241], v[100:103]
	v_mfma_f32_16x16x32_bf16 v[96:99], v[222:225], v[238:241], v[96:99]
	v_mfma_f32_16x16x32_bf16 v[84:87], v[212:215], v[246:249], v[84:87]
	v_mfma_f32_16x16x32_bf16 v[80:83], v[222:225], v[246:249], v[80:83]
	v_mfma_f32_16x16x32_bf16 v[68:71], v[212:215], v[186:189], v[68:71]
	v_mfma_f32_16x16x32_bf16 v[64:67], v[222:225], v[186:189], v[64:67]
	s_setprio 0
	s_barrier
	s_add_i32 s18, s94, s97
	v_lshl_add_u64 v[192:193], s[10:11], 0, v[132:133]
	s_mov_b32 m0, s18
	ds_read_b128 v[186:189], v204 offset:16384
	ds_read_b128 v[226:229], v204 offset:17408
	ds_read_b128 v[230:233], v204 offset:18432
	ds_read_b128 v[234:237], v204 offset:19456
	ds_read_b128 v[238:241], v204 offset:20480
	ds_read_b128 v[242:245], v204 offset:21504
	ds_read_b128 v[246:249], v204 offset:22528
	ds_read_b128 v[250:253], v204 offset:23552
	global_load_lds_dwordx4 v[192:193], off
	s_add_i32 m0, s18, 0x2000
	s_add_u32 s18, s10, 0x40000
	v_lshl_add_u64 v[196:197], s[10:11], 0, v[136:137]
	s_addc_u32 s19, s11, 0
	s_add_i32 s20, s95, s97
	global_load_lds_dwordx4 v[196:197], off
	s_mov_b32 m0, s20
	s_nop 0
	global_load_lds_dwordx4 v132, s[18:19]
	v_lshl_add_u64 v[176:177], s[18:19], 0, v[136:137]
	s_add_i32 m0, s20, 0x2000
	s_lshl_b64 s[18:19], s[86:87], 7
	s_add_u32 s18, s17, s18
	s_addc_u32 s19, s16, s19
	global_load_lds_dwordx4 v[176:177], off
	s_mov_b32 m0, s39
	s_nop 0
	global_load_lds_dwordx4 v130, s[18:19]
	s_mov_b32 m0, s91
	s_nop 0
	global_load_lds_dwordx4 v134, s[18:19]
	s_waitcnt vmcnt(8)
	s_waitcnt lgkmcnt(0)
	s_barrier
	s_setprio 1
	v_mfma_f32_16x16x32_bf16 v[60:63], v[160:163], v[186:189], v[60:63]
	v_mfma_f32_16x16x32_bf16 v[56:59], v[168:171], v[186:189], v[56:59]
	v_mfma_f32_16x16x32_bf16 v[44:47], v[160:163], v[230:233], v[44:47]
	v_mfma_f32_16x16x32_bf16 v[40:43], v[168:171], v[230:233], v[40:43]
	v_mfma_f32_16x16x32_bf16 v[28:31], v[160:163], v[238:241], v[28:31]
	v_mfma_f32_16x16x32_bf16 v[24:27], v[168:171], v[238:241], v[24:27]
	v_mfma_f32_16x16x32_bf16 v[12:15], v[160:163], v[246:249], v[12:15]
	v_mfma_f32_16x16x32_bf16 v[8:11], v[168:171], v[246:249], v[8:11]
	v_mfma_f32_16x16x32_bf16 v[60:63], v[164:167], v[226:229], v[60:63]
	v_mfma_f32_16x16x32_bf16 v[56:59], v[172:175], v[226:229], v[56:59]
	v_mfma_f32_16x16x32_bf16 v[44:47], v[164:167], v[234:237], v[44:47]
	v_mfma_f32_16x16x32_bf16 v[40:43], v[172:175], v[234:237], v[40:43]
	v_mfma_f32_16x16x32_bf16 v[28:31], v[164:167], v[242:245], v[28:31]
	v_mfma_f32_16x16x32_bf16 v[24:27], v[172:175], v[242:245], v[24:27]
	v_mfma_f32_16x16x32_bf16 v[12:15], v[164:167], v[250:253], v[12:15]
	v_mfma_f32_16x16x32_bf16 v[8:11], v[172:175], v[250:253], v[8:11]
	v_mfma_f32_16x16x32_bf16 v[52:55], v[208:211], v[186:189], v[52:55]
	v_mfma_f32_16x16x32_bf16 v[48:51], v[218:221], v[186:189], v[48:51]
	v_mfma_f32_16x16x32_bf16 v[36:39], v[208:211], v[230:233], v[36:39]
	v_mfma_f32_16x16x32_bf16 v[32:35], v[218:221], v[230:233], v[32:35]
	v_mfma_f32_16x16x32_bf16 v[20:23], v[208:211], v[238:241], v[20:23]
	v_mfma_f32_16x16x32_bf16 v[16:19], v[218:221], v[238:241], v[16:19]
	v_mfma_f32_16x16x32_bf16 v[4:7], v[208:211], v[246:249], v[4:7]
	v_mfma_f32_16x16x32_bf16 v[0:3], v[218:221], v[246:249], v[0:3]
	v_mfma_f32_16x16x32_bf16 v[52:55], v[212:215], v[226:229], v[52:55]
	v_mfma_f32_16x16x32_bf16 v[48:51], v[222:225], v[226:229], v[48:51]
	v_mfma_f32_16x16x32_bf16 v[36:39], v[212:215], v[234:237], v[36:39]
	v_mfma_f32_16x16x32_bf16 v[32:35], v[222:225], v[234:237], v[32:35]
	v_mfma_f32_16x16x32_bf16 v[20:23], v[212:215], v[242:245], v[20:23]
	v_mfma_f32_16x16x32_bf16 v[16:19], v[222:225], v[242:245], v[16:19]
	v_mfma_f32_16x16x32_bf16 v[4:7], v[212:215], v[250:253], v[4:7]
	v_mfma_f32_16x16x32_bf16 v[0:3], v[222:225], v[250:253], v[0:3]
	s_setprio 0
	s_barrier
	s_add_i32 s20, 0, 0x18000
	v_add_u32_e32 v138, s20, v179
	s_add_i32 s21, 0, 0x1c000
	ds_read_b128 v[160:163], v138
	ds_read_b128 v[164:167], v138 offset:1024
	ds_read_b128 v[168:171], v138 offset:2048
	ds_read_b128 v[172:175], v138 offset:3072
	v_add_u32_e32 v138, s21, v179
	ds_read_b128 v[186:189], v138
	ds_read_b128 v[208:211], v138 offset:1024
	ds_read_b128 v[212:215], v138 offset:2048
	ds_read_b128 v[218:221], v138 offset:3072
	s_add_u32 s18, s18, 0x40000
	s_addc_u32 s19, s19, 0
	s_mov_b32 m0, s33
	ds_read_b128 v[222:225], v204 offset:32768
	ds_read_b128 v[226:229], v204 offset:33792
	ds_read_b128 v[230:233], v204 offset:34816
	ds_read_b128 v[234:237], v204 offset:35840
	ds_read_b128 v[238:241], v204 offset:36864
	ds_read_b128 v[242:245], v204 offset:37888
	ds_read_b128 v[246:249], v204 offset:38912
	ds_read_b128 v[250:253], v204 offset:39936
	global_load_lds_dwordx4 v130, s[18:19]
	s_mov_b32 m0, s58
	s_nop 0
	global_load_lds_dwordx4 v134, s[18:19]
	s_waitcnt vmcnt(8)
	s_waitcnt lgkmcnt(0)
	s_barrier
	s_setprio 1
	v_mfma_f32_16x16x32_bf16 v[124:127], v[160:163], v[222:225], v[124:127]
	v_mfma_f32_16x16x32_bf16 v[120:123], v[168:171], v[222:225], v[120:123]
	v_mfma_f32_16x16x32_bf16 v[108:111], v[160:163], v[230:233], v[108:111]
	v_mfma_f32_16x16x32_bf16 v[104:107], v[168:171], v[230:233], v[104:107]
	v_mfma_f32_16x16x32_bf16 v[92:95], v[160:163], v[238:241], v[92:95]
	v_mfma_f32_16x16x32_bf16 v[88:91], v[168:171], v[238:241], v[88:91]
	v_mfma_f32_16x16x32_bf16 v[76:79], v[160:163], v[246:249], v[76:79]
	v_mfma_f32_16x16x32_bf16 v[72:75], v[168:171], v[246:249], v[72:75]
	v_mfma_f32_16x16x32_bf16 v[124:127], v[164:167], v[226:229], v[124:127]
	v_mfma_f32_16x16x32_bf16 v[120:123], v[172:175], v[226:229], v[120:123]
	v_mfma_f32_16x16x32_bf16 v[108:111], v[164:167], v[234:237], v[108:111]
	v_mfma_f32_16x16x32_bf16 v[104:107], v[172:175], v[234:237], v[104:107]
	v_mfma_f32_16x16x32_bf16 v[92:95], v[164:167], v[242:245], v[92:95]
	v_mfma_f32_16x16x32_bf16 v[88:91], v[172:175], v[242:245], v[88:91]
	v_mfma_f32_16x16x32_bf16 v[76:79], v[164:167], v[250:253], v[76:79]
	v_mfma_f32_16x16x32_bf16 v[72:75], v[172:175], v[250:253], v[72:75]
	v_mfma_f32_16x16x32_bf16 v[116:119], v[186:189], v[222:225], v[116:119]
	v_mfma_f32_16x16x32_bf16 v[112:115], v[212:215], v[222:225], v[112:115]
	v_mfma_f32_16x16x32_bf16 v[100:103], v[186:189], v[230:233], v[100:103]
	v_mfma_f32_16x16x32_bf16 v[96:99], v[212:215], v[230:233], v[96:99]
	v_mfma_f32_16x16x32_bf16 v[84:87], v[186:189], v[238:241], v[84:87]
	v_mfma_f32_16x16x32_bf16 v[80:83], v[212:215], v[238:241], v[80:83]
	v_mfma_f32_16x16x32_bf16 v[68:71], v[186:189], v[246:249], v[68:71]
	v_mfma_f32_16x16x32_bf16 v[64:67], v[212:215], v[246:249], v[64:67]
	v_mfma_f32_16x16x32_bf16 v[116:119], v[208:211], v[226:229], v[116:119]
	v_mfma_f32_16x16x32_bf16 v[112:115], v[218:221], v[226:229], v[112:115]
	v_mfma_f32_16x16x32_bf16 v[100:103], v[208:211], v[234:237], v[100:103]
	v_mfma_f32_16x16x32_bf16 v[96:99], v[218:221], v[234:237], v[96:99]
	v_mfma_f32_16x16x32_bf16 v[84:87], v[208:211], v[242:245], v[84:87]
	v_mfma_f32_16x16x32_bf16 v[80:83], v[218:221], v[242:245], v[80:83]
	v_mfma_f32_16x16x32_bf16 v[68:71], v[208:211], v[250:253], v[68:71]
	v_mfma_f32_16x16x32_bf16 v[64:67], v[218:221], v[250:253], v[64:67]
	s_setprio 0
	s_barrier
	s_add_i32 s18, s20, s97
	v_lshl_add_u64 v[176:177], v[192:193], 0, s[64:65]
	s_mov_b32 m0, s18
	ds_read_b128 v[222:225], v204 offset:49152
	ds_read_b128 v[226:229], v204 offset:50176
	ds_read_b128 v[230:233], v204 offset:51200
	ds_read_b128 v[234:237], v204 offset:52224
	ds_read_b128 v[238:241], v204 offset:53248
	ds_read_b128 v[242:245], v204 offset:54272
	ds_read_b128 v[246:249], v204 offset:55296
	ds_read_b128 v[250:253], v204 offset:56320
	global_load_lds_dwordx4 v[176:177], off
	s_add_i32 m0, s18, 0x2000
	s_add_u32 s10, s10, 0x40080
	v_lshl_add_u64 v[176:177], v[196:197], 0, s[64:65]
	s_addc_u32 s11, s11, 0
	s_add_i32 s18, s21, s97
	global_load_lds_dwordx4 v[176:177], off
	s_mov_b32 m0, s18
	s_or_b32 s86, s86, 1
	global_load_lds_dwordx4 v132, s[10:11]
	v_lshl_add_u64 v[176:177], s[10:11], 0, v[136:137]
	s_add_i32 m0, s18, 0x2000
	s_lshl_b64 s[10:11], s[86:87], 7
	s_add_u32 s10, s17, s10
	s_addc_u32 s11, s16, s11
	global_load_lds_dwordx4 v[176:177], off
	s_mov_b32 m0, s92
	s_nop 0
	global_load_lds_dwordx4 v130, s[10:11]
	s_mov_b32 m0, s93
	s_nop 0
	global_load_lds_dwordx4 v134, s[10:11]
	s_waitcnt vmcnt(8)
	s_waitcnt lgkmcnt(0)
	s_barrier
	s_setprio 1
	v_mfma_f32_16x16x32_bf16 v[60:63], v[160:163], v[222:225], v[60:63]
	v_mfma_f32_16x16x32_bf16 v[56:59], v[168:171], v[222:225], v[56:59]
	v_mfma_f32_16x16x32_bf16 v[44:47], v[160:163], v[230:233], v[44:47]
	v_mfma_f32_16x16x32_bf16 v[40:43], v[168:171], v[230:233], v[40:43]
	v_mfma_f32_16x16x32_bf16 v[28:31], v[160:163], v[238:241], v[28:31]
	v_mfma_f32_16x16x32_bf16 v[24:27], v[168:171], v[238:241], v[24:27]
	v_mfma_f32_16x16x32_bf16 v[12:15], v[160:163], v[246:249], v[12:15]
	v_mfma_f32_16x16x32_bf16 v[8:11], v[168:171], v[246:249], v[8:11]
	v_mfma_f32_16x16x32_bf16 v[60:63], v[164:167], v[226:229], v[60:63]
	v_mfma_f32_16x16x32_bf16 v[56:59], v[172:175], v[226:229], v[56:59]
	v_mfma_f32_16x16x32_bf16 v[44:47], v[164:167], v[234:237], v[44:47]
	v_mfma_f32_16x16x32_bf16 v[40:43], v[172:175], v[234:237], v[40:43]
	v_mfma_f32_16x16x32_bf16 v[28:31], v[164:167], v[242:245], v[28:31]
	v_mfma_f32_16x16x32_bf16 v[24:27], v[172:175], v[242:245], v[24:27]
	v_mfma_f32_16x16x32_bf16 v[12:15], v[164:167], v[250:253], v[12:15]
	v_mfma_f32_16x16x32_bf16 v[8:11], v[172:175], v[250:253], v[8:11]
	v_mfma_f32_16x16x32_bf16 v[52:55], v[186:189], v[222:225], v[52:55]
	v_mfma_f32_16x16x32_bf16 v[48:51], v[212:215], v[222:225], v[48:51]
	v_mfma_f32_16x16x32_bf16 v[36:39], v[186:189], v[230:233], v[36:39]
	v_mfma_f32_16x16x32_bf16 v[32:35], v[212:215], v[230:233], v[32:35]
	v_mfma_f32_16x16x32_bf16 v[20:23], v[186:189], v[238:241], v[20:23]
	v_mfma_f32_16x16x32_bf16 v[16:19], v[212:215], v[238:241], v[16:19]
	v_mfma_f32_16x16x32_bf16 v[4:7], v[186:189], v[246:249], v[4:7]
	v_mfma_f32_16x16x32_bf16 v[0:3], v[212:215], v[246:249], v[0:3]
	v_mfma_f32_16x16x32_bf16 v[52:55], v[208:211], v[226:229], v[52:55]
	v_mfma_f32_16x16x32_bf16 v[48:51], v[218:221], v[226:229], v[48:51]
	v_mfma_f32_16x16x32_bf16 v[36:39], v[208:211], v[234:237], v[36:39]
	v_mfma_f32_16x16x32_bf16 v[32:35], v[218:221], v[234:237], v[32:35]
	v_mfma_f32_16x16x32_bf16 v[20:23], v[208:211], v[242:245], v[20:23]
	v_mfma_f32_16x16x32_bf16 v[16:19], v[218:221], v[242:245], v[16:19]
	v_mfma_f32_16x16x32_bf16 v[4:7], v[208:211], v[250:253], v[4:7]
	v_mfma_f32_16x16x32_bf16 v[0:3], v[218:221], v[250:253], v[0:3]
	s_setprio 0
	s_barrier
	s_add_u32 s6, s6, 0x100
	s_addc_u32 s7, s7, 0
	s_cmp_gt_u32 s14, 13
	s_mov_b32 s14, s15
	s_cbranch_scc0 .LBB0_124
	s_and_b64 vcc, exec, s[66:67]
	s_cbranch_vccz .LBB0_127
	s_barrier

.LBB0_504:
	s_add_u32 s20, s31, s44
	ds_read_b128 v[132:135], v217
	ds_read_b128 v[136:139], v217 offset:1024
	ds_read_b128 v[140:143], v217 offset:2048
	ds_read_b128 v[144:147], v217 offset:3072
	ds_read_b128 v[148:151], v218
	ds_read_b128 v[152:155], v218 offset:1024
	ds_read_b128 v[156:159], v218 offset:2048
	ds_read_b128 v[160:163], v218 offset:3072
	s_addc_u32 s48, s39, s45
	s_cmpk_eq_i32 s44, 0x700
	s_cselect_b64 s[46:47], -1, 0
	s_and_b64 s[46:47], s[46:47], exec
	s_cselect_b32 s47, s19, s48
	s_cselect_b32 s46, s29, s20
	s_add_i32 s64, s63, 2
	s_cmpk_eq_i32 s44, 0x700
	s_cselect_b64 s[48:49], -1, 0
	s_and_b64 s[66:67], s[48:49], exec
	s_cselect_b32 s20, 0, s64
	s_and_b64 s[48:49], s[48:49], s[6:7]
	s_and_b64 s[48:49], s[48:49], exec
	s_cselect_b32 s48, s35, s43
	s_cselect_b32 s49, s34, s42
	v_lshl_add_u64 v[238:239], v[128:129], 0, s[44:45]
	s_add_i32 m0, s50, 0xc000
	ds_read_b128 v[164:167], v219
	ds_read_b128 v[168:171], v219 offset:1024
	ds_read_b128 v[172:175], v219 offset:2048
	ds_read_b128 v[192:195], v219 offset:3072
	ds_read_b128 v[222:225], v219 offset:4096
	ds_read_b128 v[226:229], v219 offset:5120
	ds_read_b128 v[230:233], v219 offset:6144
	ds_read_b128 v[234:237], v219 offset:7168
	global_load_lds_dwordx4 v[238:239], off
	v_lshl_add_u64 v[238:239], v[130:131], 0, s[44:45]
	s_add_i32 m0, s50, 0xe000
	s_nop 0
	global_load_lds_dwordx4 v[238:239], off
	s_waitcnt vmcnt(8)
	s_waitcnt lgkmcnt(0)
	s_barrier
	s_setprio 1
	v_mfma_f32_16x16x32_bf16 v[124:127], v[132:135], v[164:167], v[124:127]
	v_mfma_f32_16x16x32_bf16 v[120:123], v[140:143], v[164:167], v[120:123]
	v_mfma_f32_16x16x32_bf16 v[108:111], v[132:135], v[172:175], v[108:111]
	v_mfma_f32_16x16x32_bf16 v[104:107], v[140:143], v[172:175], v[104:107]
	v_mfma_f32_16x16x32_bf16 v[92:95], v[132:135], v[222:225], v[92:95]
	v_mfma_f32_16x16x32_bf16 v[88:91], v[140:143], v[222:225], v[88:91]
	v_mfma_f32_16x16x32_bf16 v[76:79], v[132:135], v[230:233], v[76:79]
	v_mfma_f32_16x16x32_bf16 v[72:75], v[140:143], v[230:233], v[72:75]
	v_mfma_f32_16x16x32_bf16 v[124:127], v[136:139], v[168:171], v[124:127]
	v_mfma_f32_16x16x32_bf16 v[120:123], v[144:147], v[168:171], v[120:123]
	v_mfma_f32_16x16x32_bf16 v[108:111], v[136:139], v[192:195], v[108:111]
	v_mfma_f32_16x16x32_bf16 v[104:107], v[144:147], v[192:195], v[104:107]
	v_mfma_f32_16x16x32_bf16 v[92:95], v[136:139], v[226:229], v[92:95]
	v_mfma_f32_16x16x32_bf16 v[88:91], v[144:147], v[226:229], v[88:91]
	v_mfma_f32_16x16x32_bf16 v[76:79], v[136:139], v[234:237], v[76:79]
	v_mfma_f32_16x16x32_bf16 v[72:75], v[144:147], v[234:237], v[72:75]
	v_mfma_f32_16x16x32_bf16 v[116:119], v[148:151], v[164:167], v[116:119]
	v_mfma_f32_16x16x32_bf16 v[112:115], v[156:159], v[164:167], v[112:115]
	v_mfma_f32_16x16x32_bf16 v[100:103], v[148:151], v[172:175], v[100:103]
	v_mfma_f32_16x16x32_bf16 v[96:99], v[156:159], v[172:175], v[96:99]
	v_mfma_f32_16x16x32_bf16 v[84:87], v[148:151], v[222:225], v[84:87]
	v_mfma_f32_16x16x32_bf16 v[80:83], v[156:159], v[222:225], v[80:83]
	v_mfma_f32_16x16x32_bf16 v[68:71], v[148:151], v[230:233], v[68:71]
	v_mfma_f32_16x16x32_bf16 v[64:67], v[156:159], v[230:233], v[64:67]
	v_mfma_f32_16x16x32_bf16 v[116:119], v[152:155], v[168:171], v[116:119]
	v_mfma_f32_16x16x32_bf16 v[112:115], v[160:163], v[168:171], v[112:115]
	v_mfma_f32_16x16x32_bf16 v[100:103], v[152:155], v[192:195], v[100:103]
	v_mfma_f32_16x16x32_bf16 v[96:99], v[160:163], v[192:195], v[96:99]
	v_mfma_f32_16x16x32_bf16 v[84:87], v[152:155], v[226:229], v[84:87]
	v_mfma_f32_16x16x32_bf16 v[80:83], v[160:163], v[226:229], v[80:83]
	v_mfma_f32_16x16x32_bf16 v[68:71], v[152:155], v[234:237], v[68:71]
	v_mfma_f32_16x16x32_bf16 v[64:67], v[160:163], v[234:237], v[64:67]
	s_setprio 0
	s_barrier
	s_add_i32 s65, s58, s33
	v_lshl_add_u64 v[238:239], s[46:47], 0, v[178:179]
	s_mov_b32 m0, s65
	ds_read_b128 v[164:167], v219 offset:16384
	ds_read_b128 v[168:171], v219 offset:17408
	ds_read_b128 v[172:175], v219 offset:18432
	ds_read_b128 v[192:195], v219 offset:19456
	ds_read_b128 v[222:225], v219 offset:20480
	ds_read_b128 v[226:229], v219 offset:21504
	ds_read_b128 v[230:233], v219 offset:22528
	ds_read_b128 v[234:237], v219 offset:23552
	global_load_lds_dwordx4 v[238:239], off
	s_add_i32 m0, s65, 0x2000
	s_add_u32 s66, s46, 0x40000
	v_lshl_add_u64 v[240:241], s[46:47], 0, v[182:183]
	s_addc_u32 s67, s47, 0
	s_add_i32 s65, s59, s33
	global_load_lds_dwordx4 v[240:241], off
	v_lshl_add_u64 v[242:243], s[66:67], 0, v[178:179]
	s_mov_b32 m0, s65
	s_nop 0
	global_load_lds_dwordx4 v[242:243], off
	v_lshl_add_u64 v[242:243], s[66:67], 0, v[182:183]
	s_add_i32 m0, s65, 0x2000
	s_lshl_b64 s[66:67], s[20:21], 7
	s_add_u32 s66, s49, s66
	s_addc_u32 s67, s48, s67
	global_load_lds_dwordx4 v[242:243], off
	v_lshl_add_u64 v[242:243], s[66:67], 0, v[176:177]
	s_mov_b32 m0, s50
	s_nop 0
	global_load_lds_dwordx4 v[242:243], off
	v_lshl_add_u64 v[242:243], s[66:67], 0, v[180:181]
	s_mov_b32 m0, s51
	s_nop 0
	global_load_lds_dwordx4 v[242:243], off
	s_waitcnt vmcnt(8)
	s_waitcnt lgkmcnt(0)
	s_barrier
	s_setprio 1
	v_mfma_f32_16x16x32_bf16 v[60:63], v[132:135], v[164:167], v[60:63]
	v_mfma_f32_16x16x32_bf16 v[56:59], v[140:143], v[164:167], v[56:59]
	v_mfma_f32_16x16x32_bf16 v[44:47], v[132:135], v[172:175], v[44:47]
	v_mfma_f32_16x16x32_bf16 v[40:43], v[140:143], v[172:175], v[40:43]
	v_mfma_f32_16x16x32_bf16 v[28:31], v[132:135], v[222:225], v[28:31]
	v_mfma_f32_16x16x32_bf16 v[24:27], v[140:143], v[222:225], v[24:27]
	v_mfma_f32_16x16x32_bf16 v[12:15], v[132:135], v[230:233], v[12:15]
	v_mfma_f32_16x16x32_bf16 v[8:11], v[140:143], v[230:233], v[8:11]
	v_mfma_f32_16x16x32_bf16 v[60:63], v[136:139], v[168:171], v[60:63]
	v_mfma_f32_16x16x32_bf16 v[56:59], v[144:147], v[168:171], v[56:59]
	v_mfma_f32_16x16x32_bf16 v[44:47], v[136:139], v[192:195], v[44:47]
	v_mfma_f32_16x16x32_bf16 v[40:43], v[144:147], v[192:195], v[40:43]
	v_mfma_f32_16x16x32_bf16 v[28:31], v[136:139], v[226:229], v[28:31]
	v_mfma_f32_16x16x32_bf16 v[24:27], v[144:147], v[226:229], v[24:27]
	v_mfma_f32_16x16x32_bf16 v[12:15], v[136:139], v[234:237], v[12:15]
	v_mfma_f32_16x16x32_bf16 v[8:11], v[144:147], v[234:237], v[8:11]
	v_mfma_f32_16x16x32_bf16 v[52:55], v[148:151], v[164:167], v[52:55]
	v_mfma_f32_16x16x32_bf16 v[48:51], v[156:159], v[164:167], v[48:51]
	v_mfma_f32_16x16x32_bf16 v[36:39], v[148:151], v[172:175], v[36:39]
	v_mfma_f32_16x16x32_bf16 v[32:35], v[156:159], v[172:175], v[32:35]
	v_mfma_f32_16x16x32_bf16 v[20:23], v[148:151], v[222:225], v[20:23]
	v_mfma_f32_16x16x32_bf16 v[16:19], v[156:159], v[222:225], v[16:19]
	v_mfma_f32_16x16x32_bf16 v[4:7], v[148:151], v[230:233], v[4:7]
	v_mfma_f32_16x16x32_bf16 v[0:3], v[156:159], v[230:233], v[0:3]
	v_mfma_f32_16x16x32_bf16 v[52:55], v[152:155], v[168:171], v[52:55]
	v_mfma_f32_16x16x32_bf16 v[48:51], v[160:163], v[168:171], v[48:51]
	v_mfma_f32_16x16x32_bf16 v[36:39], v[152:155], v[192:195], v[36:39]
	v_mfma_f32_16x16x32_bf16 v[32:35], v[160:163], v[192:195], v[32:35]
	v_mfma_f32_16x16x32_bf16 v[20:23], v[152:155], v[226:229], v[20:23]
	v_mfma_f32_16x16x32_bf16 v[16:19], v[160:163], v[226:229], v[16:19]
	v_mfma_f32_16x16x32_bf16 v[4:7], v[152:155], v[234:237], v[4:7]
	v_mfma_f32_16x16x32_bf16 v[0:3], v[160:163], v[234:237], v[0:3]
	s_setprio 0
	s_barrier
	s_add_i32 s65, 0, 0x18000
	s_add_i32 s68, 0, 0x1c000
	v_add_u32_e32 v144, s65, v198
	v_add_u32_e32 v160, s68, v198
	ds_read_b128 v[132:135], v144
	ds_read_b128 v[136:139], v144 offset:1024
	ds_read_b128 v[140:143], v144 offset:2048
	ds_read_b128 v[144:147], v144 offset:3072
	ds_read_b128 v[148:151], v160
	ds_read_b128 v[152:155], v160 offset:1024
	ds_read_b128 v[156:159], v160 offset:2048
	ds_read_b128 v[160:163], v160 offset:3072
	s_add_u32 s66, s66, 0x40000
	s_addc_u32 s67, s67, 0
	s_mov_b32 m0, s52
	v_lshl_add_u64 v[242:243], s[66:67], 0, v[176:177]
	ds_read_b128 v[164:167], v219 offset:32768
	ds_read_b128 v[168:171], v219 offset:33792
	ds_read_b128 v[172:175], v219 offset:34816
	ds_read_b128 v[192:195], v219 offset:35840
	ds_read_b128 v[222:225], v219 offset:36864
	ds_read_b128 v[226:229], v219 offset:37888
	ds_read_b128 v[230:233], v219 offset:38912
	ds_read_b128 v[234:237], v219 offset:39936
	global_load_lds_dwordx4 v[242:243], off
	v_lshl_add_u64 v[242:243], s[66:67], 0, v[180:181]
	s_mov_b32 m0, s53
	s_nop 0
	global_load_lds_dwordx4 v[242:243], off
	s_waitcnt vmcnt(8)
	s_waitcnt lgkmcnt(0)
	s_barrier
	s_setprio 1
	v_mfma_f32_16x16x32_bf16 v[124:127], v[132:135], v[164:167], v[124:127]
	v_mfma_f32_16x16x32_bf16 v[120:123], v[140:143], v[164:167], v[120:123]
	v_mfma_f32_16x16x32_bf16 v[108:111], v[132:135], v[172:175], v[108:111]
	v_mfma_f32_16x16x32_bf16 v[104:107], v[140:143], v[172:175], v[104:107]
	v_mfma_f32_16x16x32_bf16 v[92:95], v[132:135], v[222:225], v[92:95]
	v_mfma_f32_16x16x32_bf16 v[88:91], v[140:143], v[222:225], v[88:91]
	v_mfma_f32_16x16x32_bf16 v[76:79], v[132:135], v[230:233], v[76:79]
	v_mfma_f32_16x16x32_bf16 v[72:75], v[140:143], v[230:233], v[72:75]
	v_mfma_f32_16x16x32_bf16 v[124:127], v[136:139], v[168:171], v[124:127]
	v_mfma_f32_16x16x32_bf16 v[120:123], v[144:147], v[168:171], v[120:123]
	v_mfma_f32_16x16x32_bf16 v[108:111], v[136:139], v[192:195], v[108:111]
	v_mfma_f32_16x16x32_bf16 v[104:107], v[144:147], v[192:195], v[104:107]
	v_mfma_f32_16x16x32_bf16 v[92:95], v[136:139], v[226:229], v[92:95]
	v_mfma_f32_16x16x32_bf16 v[88:91], v[144:147], v[226:229], v[88:91]
	v_mfma_f32_16x16x32_bf16 v[76:79], v[136:139], v[234:237], v[76:79]
	v_mfma_f32_16x16x32_bf16 v[72:75], v[144:147], v[234:237], v[72:75]
	v_mfma_f32_16x16x32_bf16 v[116:119], v[148:151], v[164:167], v[116:119]
	v_mfma_f32_16x16x32_bf16 v[112:115], v[156:159], v[164:167], v[112:115]
	v_mfma_f32_16x16x32_bf16 v[100:103], v[148:151], v[172:175], v[100:103]
	v_mfma_f32_16x16x32_bf16 v[96:99], v[156:159], v[172:175], v[96:99]
	v_mfma_f32_16x16x32_bf16 v[84:87], v[148:151], v[222:225], v[84:87]
	v_mfma_f32_16x16x32_bf16 v[80:83], v[156:159], v[222:225], v[80:83]
	v_mfma_f32_16x16x32_bf16 v[68:71], v[148:151], v[230:233], v[68:71]
	v_mfma_f32_16x16x32_bf16 v[64:67], v[156:159], v[230:233], v[64:67]
	v_mfma_f32_16x16x32_bf16 v[116:119], v[152:155], v[168:171], v[116:119]
	v_mfma_f32_16x16x32_bf16 v[112:115], v[160:163], v[168:171], v[112:115]
	v_mfma_f32_16x16x32_bf16 v[100:103], v[152:155], v[192:195], v[100:103]
	v_mfma_f32_16x16x32_bf16 v[96:99], v[160:163], v[192:195], v[96:99]
	v_mfma_f32_16x16x32_bf16 v[84:87], v[152:155], v[226:229], v[84:87]
	v_mfma_f32_16x16x32_bf16 v[80:83], v[160:163], v[226:229], v[80:83]
	v_mfma_f32_16x16x32_bf16 v[68:71], v[152:155], v[234:237], v[68:71]
	v_mfma_f32_16x16x32_bf16 v[64:67], v[160:163], v[234:237], v[64:67]
	s_setprio 0
	s_barrier
	s_add_i32 s65, s65, s33
	v_lshl_add_u64 v[238:239], v[238:239], 0, s[24:25]
	s_mov_b32 m0, s65
	ds_read_b128 v[164:167], v219 offset:49152
	ds_read_b128 v[168:171], v219 offset:50176
	ds_read_b128 v[172:175], v219 offset:51200
	ds_read_b128 v[192:195], v219 offset:52224
	ds_read_b128 v[222:225], v219 offset:53248
	ds_read_b128 v[226:229], v219 offset:54272
	ds_read_b128 v[230:233], v219 offset:55296
	ds_read_b128 v[234:237], v219 offset:56320
	global_load_lds_dwordx4 v[238:239], off
	s_add_i32 m0, s65, 0x2000
	s_add_u32 s46, s46, 0x40080
	v_lshl_add_u64 v[238:239], v[240:241], 0, s[24:25]
	s_addc_u32 s47, s47, 0
	s_add_i32 s65, s68, s33
	global_load_lds_dwordx4 v[238:239], off
	s_mov_b32 m0, s65
	s_or_b32 s20, s20, 1
	global_load_lds_dwordx4 v178, s[46:47]
	v_lshl_add_u64 v[238:239], s[46:47], 0, v[182:183]
	s_add_i32 m0, s65, 0x2000
	s_lshl_b64 s[46:47], s[20:21], 7
	s_add_u32 s46, s49, s46
	s_addc_u32 s47, s48, s47
	global_load_lds_dwordx4 v[238:239], off
	s_mov_b32 m0, s56
	s_nop 0
	global_load_lds_dwordx4 v176, s[46:47]
	s_mov_b32 m0, s57
	s_nop 0
	global_load_lds_dwordx4 v180, s[46:47]
	s_waitcnt vmcnt(8)
	s_waitcnt lgkmcnt(0)
	s_barrier
	s_setprio 1
	v_mfma_f32_16x16x32_bf16 v[60:63], v[132:135], v[164:167], v[60:63]
	v_mfma_f32_16x16x32_bf16 v[56:59], v[140:143], v[164:167], v[56:59]
	v_mfma_f32_16x16x32_bf16 v[44:47], v[132:135], v[172:175], v[44:47]
	v_mfma_f32_16x16x32_bf16 v[40:43], v[140:143], v[172:175], v[40:43]
	v_mfma_f32_16x16x32_bf16 v[28:31], v[132:135], v[222:225], v[28:31]
	v_mfma_f32_16x16x32_bf16 v[24:27], v[140:143], v[222:225], v[24:27]
	v_mfma_f32_16x16x32_bf16 v[12:15], v[132:135], v[230:233], v[12:15]
	v_mfma_f32_16x16x32_bf16 v[8:11], v[140:143], v[230:233], v[8:11]
	v_mfma_f32_16x16x32_bf16 v[60:63], v[136:139], v[168:171], v[60:63]
	v_mfma_f32_16x16x32_bf16 v[56:59], v[144:147], v[168:171], v[56:59]
	v_mfma_f32_16x16x32_bf16 v[44:47], v[136:139], v[192:195], v[44:47]
	v_mfma_f32_16x16x32_bf16 v[40:43], v[144:147], v[192:195], v[40:43]
	v_mfma_f32_16x16x32_bf16 v[28:31], v[136:139], v[226:229], v[28:31]
	v_mfma_f32_16x16x32_bf16 v[24:27], v[144:147], v[226:229], v[24:27]
	v_mfma_f32_16x16x32_bf16 v[12:15], v[136:139], v[234:237], v[12:15]
	v_mfma_f32_16x16x32_bf16 v[8:11], v[144:147], v[234:237], v[8:11]
	v_mfma_f32_16x16x32_bf16 v[52:55], v[148:151], v[164:167], v[52:55]
	v_mfma_f32_16x16x32_bf16 v[48:51], v[156:159], v[164:167], v[48:51]
	v_mfma_f32_16x16x32_bf16 v[36:39], v[148:151], v[172:175], v[36:39]
	v_mfma_f32_16x16x32_bf16 v[32:35], v[156:159], v[172:175], v[32:35]
	v_mfma_f32_16x16x32_bf16 v[20:23], v[148:151], v[222:225], v[20:23]
	v_mfma_f32_16x16x32_bf16 v[16:19], v[156:159], v[222:225], v[16:19]
	v_mfma_f32_16x16x32_bf16 v[4:7], v[148:151], v[230:233], v[4:7]
	v_mfma_f32_16x16x32_bf16 v[0:3], v[156:159], v[230:233], v[0:3]
	v_mfma_f32_16x16x32_bf16 v[52:55], v[152:155], v[168:171], v[52:55]
	v_mfma_f32_16x16x32_bf16 v[48:51], v[160:163], v[168:171], v[48:51]
	v_mfma_f32_16x16x32_bf16 v[36:39], v[152:155], v[192:195], v[36:39]
	v_mfma_f32_16x16x32_bf16 v[32:35], v[160:163], v[192:195], v[32:35]
	v_mfma_f32_16x16x32_bf16 v[20:23], v[152:155], v[226:229], v[20:23]
	v_mfma_f32_16x16x32_bf16 v[16:19], v[160:163], v[226:229], v[16:19]
	v_mfma_f32_16x16x32_bf16 v[4:7], v[152:155], v[234:237], v[4:7]
	v_mfma_f32_16x16x32_bf16 v[0:3], v[160:163], v[234:237], v[0:3]
	s_setprio 0
	s_barrier
	s_add_u32 s44, s44, 0x100
	s_addc_u32 s45, s45, 0
	s_cmp_gt_u32 s63, 13
	s_mov_b32 s63, s64
	s_cbranch_scc0 .LBB0_504
	s_and_b64 vcc, exec, s[26:27]
	s_cbranch_vccz .LBB0_507
	s_barrier

.LBB0_678:
	ds_read_b128 v[144:147], v193
	ds_read_b128 v[148:151], v193 offset:1024
	ds_read_b128 v[152:155], v193 offset:2048
	ds_read_b128 v[156:159], v193 offset:3072
	ds_read_b128 v[160:163], v194
	ds_read_b128 v[164:167], v194 offset:1024
	ds_read_b128 v[168:171], v194 offset:2048
	ds_read_b128 v[172:175], v194 offset:3072
	s_cmp_eq_u32 s22, 0x7e04000
	s_cselect_b64 s[24:25], -1, 0
	s_and_b64 s[24:25], s[24:25], exec
	s_cselect_b32 s25, s9, s43
	s_cselect_b32 s24, s11, s42
	s_add_i32 s45, s44, 2
	s_cmp_eq_u32 s22, 0x7e04000
	s_cselect_b64 s[26:27], -1, 0
	s_and_b64 s[46:47], s[26:27], exec
	s_cselect_b32 s6, 0, s45
	s_and_b64 s[26:27], s[26:27], s[4:5]
	s_and_b64 s[26:27], s[26:27], exec
	s_cselect_b32 s26, s15, s21
	s_cselect_b32 s27, s14, s20
	v_lshl_add_u64 v[188:189], v[140:141], 0, s[22:23]
	s_add_i32 m0, s19, 0xc000
	ds_read_b128 v[176:179], v195
	ds_read_b128 v[180:183], v195 offset:1024
	ds_read_b128 v[184:187], v195 offset:2048
	ds_read_b128 v[196:199], v195 offset:3072
	ds_read_b128 v[200:203], v195 offset:4096
	ds_read_b128 v[204:207], v195 offset:5120
	ds_read_b128 v[208:211], v195 offset:6144
	ds_read_b128 v[212:215], v195 offset:7168
	global_load_lds_dwordx4 v[188:189], off
	v_lshl_add_u64 v[188:189], v[142:143], 0, s[22:23]
	s_add_i32 m0, s19, 0xe000
	s_nop 0
	global_load_lds_dwordx4 v[188:189], off
	s_waitcnt vmcnt(8)
	s_waitcnt lgkmcnt(0)
	s_barrier
	s_setprio 1
	v_mfma_f32_16x16x32_bf16 v[124:127], v[144:147], v[176:179], v[124:127]
	v_mfma_f32_16x16x32_bf16 v[120:123], v[152:155], v[176:179], v[120:123]
	v_mfma_f32_16x16x32_bf16 v[112:115], v[144:147], v[184:187], v[112:115]
	v_mfma_f32_16x16x32_bf16 v[104:107], v[152:155], v[184:187], v[104:107]
	v_mfma_f32_16x16x32_bf16 v[96:99], v[144:147], v[200:203], v[96:99]
	v_mfma_f32_16x16x32_bf16 v[88:91], v[152:155], v[200:203], v[88:91]
	v_mfma_f32_16x16x32_bf16 v[80:83], v[144:147], v[208:211], v[80:83]
	v_mfma_f32_16x16x32_bf16 v[72:75], v[152:155], v[208:211], v[72:75]
	v_mfma_f32_16x16x32_bf16 v[124:127], v[148:151], v[180:183], v[124:127]
	v_mfma_f32_16x16x32_bf16 v[120:123], v[156:159], v[180:183], v[120:123]
	v_mfma_f32_16x16x32_bf16 v[112:115], v[148:151], v[196:199], v[112:115]
	v_mfma_f32_16x16x32_bf16 v[104:107], v[156:159], v[196:199], v[104:107]
	v_mfma_f32_16x16x32_bf16 v[96:99], v[148:151], v[204:207], v[96:99]
	v_mfma_f32_16x16x32_bf16 v[88:91], v[156:159], v[204:207], v[88:91]
	v_mfma_f32_16x16x32_bf16 v[80:83], v[148:151], v[212:215], v[80:83]
	v_mfma_f32_16x16x32_bf16 v[72:75], v[156:159], v[212:215], v[72:75]
	v_mfma_f32_16x16x32_bf16 v[116:119], v[160:163], v[176:179], v[116:119]
	v_mfma_f32_16x16x32_bf16 v[108:111], v[168:171], v[176:179], v[108:111]
	v_mfma_f32_16x16x32_bf16 v[100:103], v[160:163], v[184:187], v[100:103]
	v_mfma_f32_16x16x32_bf16 v[92:95], v[168:171], v[184:187], v[92:95]
	v_mfma_f32_16x16x32_bf16 v[84:87], v[160:163], v[200:203], v[84:87]
	v_mfma_f32_16x16x32_bf16 v[76:79], v[168:171], v[200:203], v[76:79]
	v_mfma_f32_16x16x32_bf16 v[68:71], v[160:163], v[208:211], v[68:71]
	v_mfma_f32_16x16x32_bf16 v[64:67], v[168:171], v[208:211], v[64:67]
	v_mfma_f32_16x16x32_bf16 v[116:119], v[164:167], v[180:183], v[116:119]
	v_mfma_f32_16x16x32_bf16 v[108:111], v[172:175], v[180:183], v[108:111]
	v_mfma_f32_16x16x32_bf16 v[100:103], v[164:167], v[196:199], v[100:103]
	v_mfma_f32_16x16x32_bf16 v[92:95], v[172:175], v[196:199], v[92:95]
	v_mfma_f32_16x16x32_bf16 v[84:87], v[164:167], v[204:207], v[84:87]
	v_mfma_f32_16x16x32_bf16 v[76:79], v[172:175], v[204:207], v[76:79]
	v_mfma_f32_16x16x32_bf16 v[68:71], v[164:167], v[212:215], v[68:71]
	v_mfma_f32_16x16x32_bf16 v[64:67], v[172:175], v[212:215], v[64:67]
	s_setprio 0
	s_barrier
	s_add_i32 s46, s38, s29
	v_lshl_add_u64 v[188:189], s[24:25], 0, v[128:129]
	s_mov_b32 m0, s46
	ds_read_b128 v[176:179], v195 offset:16384
	ds_read_b128 v[180:183], v195 offset:17408
	ds_read_b128 v[184:187], v195 offset:18432
	ds_read_b128 v[196:199], v195 offset:19456
	ds_read_b128 v[200:203], v195 offset:20480
	ds_read_b128 v[204:207], v195 offset:21504
	ds_read_b128 v[208:211], v195 offset:22528
	ds_read_b128 v[212:215], v195 offset:23552
	global_load_lds_dwordx4 v[188:189], off
	s_add_i32 m0, s46, 0x2000
	s_add_u32 s46, s24, 0x4000
	s_addc_u32 s47, s25, 0
	s_add_i32 s48, s39, s29
	global_load_lds_dwordx4 v130, s[24:25]
	s_mov_b32 m0, s48
	s_nop 0
	global_load_lds_dwordx4 v128, s[46:47]
	v_lshl_add_u64 v[188:189], s[46:47], 0, v[130:131]
	s_add_i32 m0, s48, 0x2000
	s_lshl_b64 s[46:47], s[6:7], 21
	s_add_u32 s46, s27, s46
	s_addc_u32 s47, s26, s47
	global_load_lds_dwordx4 v[188:189], off
	s_mov_b32 m0, s19
	s_nop 0
	global_load_lds_dwordx4 v128, s[46:47]
	s_mov_b32 m0, s31
	s_nop 0
	global_load_lds_dwordx4 v130, s[46:47]
	s_waitcnt vmcnt(8)
	s_waitcnt lgkmcnt(0)
	s_barrier
	s_setprio 1
	v_mfma_f32_16x16x32_bf16 v[60:63], v[144:147], v[176:179], v[60:63]
	v_mfma_f32_16x16x32_bf16 v[56:59], v[152:155], v[176:179], v[56:59]
	v_mfma_f32_16x16x32_bf16 v[48:51], v[144:147], v[184:187], v[48:51]
	v_mfma_f32_16x16x32_bf16 v[40:43], v[152:155], v[184:187], v[40:43]
	v_mfma_f32_16x16x32_bf16 v[32:35], v[144:147], v[200:203], v[32:35]
	v_mfma_f32_16x16x32_bf16 v[24:27], v[152:155], v[200:203], v[24:27]
	v_mfma_f32_16x16x32_bf16 v[16:19], v[144:147], v[208:211], v[16:19]
	v_mfma_f32_16x16x32_bf16 v[8:11], v[152:155], v[208:211], v[8:11]
	v_mfma_f32_16x16x32_bf16 v[60:63], v[148:151], v[180:183], v[60:63]
	v_mfma_f32_16x16x32_bf16 v[56:59], v[156:159], v[180:183], v[56:59]
	v_mfma_f32_16x16x32_bf16 v[48:51], v[148:151], v[196:199], v[48:51]
	v_mfma_f32_16x16x32_bf16 v[40:43], v[156:159], v[196:199], v[40:43]
	v_mfma_f32_16x16x32_bf16 v[32:35], v[148:151], v[204:207], v[32:35]
	v_mfma_f32_16x16x32_bf16 v[24:27], v[156:159], v[204:207], v[24:27]
	v_mfma_f32_16x16x32_bf16 v[16:19], v[148:151], v[212:215], v[16:19]
	v_mfma_f32_16x16x32_bf16 v[8:11], v[156:159], v[212:215], v[8:11]
	v_mfma_f32_16x16x32_bf16 v[52:55], v[160:163], v[176:179], v[52:55]
	v_mfma_f32_16x16x32_bf16 v[44:47], v[168:171], v[176:179], v[44:47]
	v_mfma_f32_16x16x32_bf16 v[36:39], v[160:163], v[184:187], v[36:39]
	v_mfma_f32_16x16x32_bf16 v[28:31], v[168:171], v[184:187], v[28:31]
	v_mfma_f32_16x16x32_bf16 v[20:23], v[160:163], v[200:203], v[20:23]
	v_mfma_f32_16x16x32_bf16 v[12:15], v[168:171], v[200:203], v[12:15]
	v_mfma_f32_16x16x32_bf16 v[4:7], v[160:163], v[208:211], v[4:7]
	v_mfma_f32_16x16x32_bf16 v[0:3], v[168:171], v[208:211], v[0:3]
	v_mfma_f32_16x16x32_bf16 v[52:55], v[164:167], v[180:183], v[52:55]
	v_mfma_f32_16x16x32_bf16 v[44:47], v[172:175], v[180:183], v[44:47]
	v_mfma_f32_16x16x32_bf16 v[36:39], v[164:167], v[196:199], v[36:39]
	v_mfma_f32_16x16x32_bf16 v[28:31], v[172:175], v[196:199], v[28:31]
	v_mfma_f32_16x16x32_bf16 v[20:23], v[164:167], v[204:207], v[20:23]
	v_mfma_f32_16x16x32_bf16 v[12:15], v[172:175], v[204:207], v[12:15]
	v_mfma_f32_16x16x32_bf16 v[4:7], v[164:167], v[212:215], v[4:7]
	v_mfma_f32_16x16x32_bf16 v[0:3], v[172:175], v[212:215], v[0:3]
	s_setprio 0
	s_barrier
	s_add_i32 s48, 0, 0x18000
	s_add_i32 s49, 0, 0x1c000
	v_add_u32_e32 v156, s48, v191
	v_add_u32_e32 v172, s49, v191
	ds_read_b128 v[144:147], v156
	ds_read_b128 v[148:151], v156 offset:1024
	ds_read_b128 v[152:155], v156 offset:2048
	ds_read_b128 v[156:159], v156 offset:3072
	ds_read_b128 v[160:163], v172
	ds_read_b128 v[164:167], v172 offset:1024
	ds_read_b128 v[168:171], v172 offset:2048
	ds_read_b128 v[172:175], v172 offset:3072
	s_add_u32 s46, s46, 0x4000
	s_addc_u32 s47, s47, 0
	s_mov_b32 m0, s33
	ds_read_b128 v[176:179], v195 offset:32768
	ds_read_b128 v[180:183], v195 offset:33792
	ds_read_b128 v[184:187], v195 offset:34816
	ds_read_b128 v[196:199], v195 offset:35840
	ds_read_b128 v[200:203], v195 offset:36864
	ds_read_b128 v[204:207], v195 offset:37888
	ds_read_b128 v[208:211], v195 offset:38912
	ds_read_b128 v[212:215], v195 offset:39936
	global_load_lds_dwordx4 v128, s[46:47]
	s_mov_b32 m0, s34
	s_nop 0
	global_load_lds_dwordx4 v130, s[46:47]
	s_waitcnt vmcnt(8)
	s_waitcnt lgkmcnt(0)
	s_barrier
	s_setprio 1
	v_mfma_f32_16x16x32_bf16 v[124:127], v[144:147], v[176:179], v[124:127]
	v_mfma_f32_16x16x32_bf16 v[120:123], v[152:155], v[176:179], v[120:123]
	v_mfma_f32_16x16x32_bf16 v[112:115], v[144:147], v[184:187], v[112:115]
	v_mfma_f32_16x16x32_bf16 v[104:107], v[152:155], v[184:187], v[104:107]
	v_mfma_f32_16x16x32_bf16 v[96:99], v[144:147], v[200:203], v[96:99]
	v_mfma_f32_16x16x32_bf16 v[88:91], v[152:155], v[200:203], v[88:91]
	v_mfma_f32_16x16x32_bf16 v[80:83], v[144:147], v[208:211], v[80:83]
	v_mfma_f32_16x16x32_bf16 v[72:75], v[152:155], v[208:211], v[72:75]
	v_mfma_f32_16x16x32_bf16 v[124:127], v[148:151], v[180:183], v[124:127]
	v_mfma_f32_16x16x32_bf16 v[120:123], v[156:159], v[180:183], v[120:123]
	v_mfma_f32_16x16x32_bf16 v[112:115], v[148:151], v[196:199], v[112:115]
	v_mfma_f32_16x16x32_bf16 v[104:107], v[156:159], v[196:199], v[104:107]
	v_mfma_f32_16x16x32_bf16 v[96:99], v[148:151], v[204:207], v[96:99]
	v_mfma_f32_16x16x32_bf16 v[88:91], v[156:159], v[204:207], v[88:91]
	v_mfma_f32_16x16x32_bf16 v[80:83], v[148:151], v[212:215], v[80:83]
	v_mfma_f32_16x16x32_bf16 v[72:75], v[156:159], v[212:215], v[72:75]
	v_mfma_f32_16x16x32_bf16 v[116:119], v[160:163], v[176:179], v[116:119]
	v_mfma_f32_16x16x32_bf16 v[108:111], v[168:171], v[176:179], v[108:111]
	v_mfma_f32_16x16x32_bf16 v[100:103], v[160:163], v[184:187], v[100:103]
	v_mfma_f32_16x16x32_bf16 v[92:95], v[168:171], v[184:187], v[92:95]
	v_mfma_f32_16x16x32_bf16 v[84:87], v[160:163], v[200:203], v[84:87]
	v_mfma_f32_16x16x32_bf16 v[76:79], v[168:171], v[200:203], v[76:79]
	v_mfma_f32_16x16x32_bf16 v[68:71], v[160:163], v[208:211], v[68:71]
	v_mfma_f32_16x16x32_bf16 v[64:67], v[168:171], v[208:211], v[64:67]
	v_mfma_f32_16x16x32_bf16 v[116:119], v[164:167], v[180:183], v[116:119]
	v_mfma_f32_16x16x32_bf16 v[108:111], v[172:175], v[180:183], v[108:111]
	v_mfma_f32_16x16x32_bf16 v[100:103], v[164:167], v[196:199], v[100:103]
	v_mfma_f32_16x16x32_bf16 v[92:95], v[172:175], v[196:199], v[92:95]
	v_mfma_f32_16x16x32_bf16 v[84:87], v[164:167], v[204:207], v[84:87]
	v_mfma_f32_16x16x32_bf16 v[76:79], v[172:175], v[204:207], v[76:79]
	v_mfma_f32_16x16x32_bf16 v[68:71], v[164:167], v[212:215], v[68:71]
	v_mfma_f32_16x16x32_bf16 v[64:67], v[172:175], v[212:215], v[64:67]
	s_setprio 0
	s_barrier
	s_add_u32 s46, s24, 0x20000
	s_addc_u32 s47, s25, 0
	s_add_i32 s48, s48, s29
	v_lshl_add_u64 v[188:189], s[46:47], 0, v[128:129]
	s_mov_b32 m0, s48
	ds_read_b128 v[176:179], v195 offset:49152
	ds_read_b128 v[180:183], v195 offset:50176
	ds_read_b128 v[184:187], v195 offset:51200
	ds_read_b128 v[196:199], v195 offset:52224
	ds_read_b128 v[200:203], v195 offset:53248
	ds_read_b128 v[204:207], v195 offset:54272
	ds_read_b128 v[208:211], v195 offset:55296
	ds_read_b128 v[212:215], v195 offset:56320
	global_load_lds_dwordx4 v[188:189], off
	s_add_i32 m0, s48, 0x2000
	s_add_u32 s24, s24, 0x24000
	v_lshl_add_u64 v[188:189], s[46:47], 0, v[130:131]
	s_addc_u32 s25, s25, 0
	s_add_i32 s46, s49, s29
	global_load_lds_dwordx4 v[188:189], off
	s_mov_b32 m0, s46
	s_or_b32 s6, s6, 1
	global_load_lds_dwordx4 v128, s[24:25]
	v_lshl_add_u64 v[188:189], s[24:25], 0, v[130:131]
	s_add_i32 m0, s46, 0x2000
	s_lshl_b64 s[24:25], s[6:7], 21
	s_add_u32 s24, s27, s24
	s_addc_u32 s25, s26, s25
	global_load_lds_dwordx4 v[188:189], off
	s_mov_b32 m0, s36
	s_nop 0
	global_load_lds_dwordx4 v128, s[24:25]
	s_mov_b32 m0, s37
	s_nop 0
	global_load_lds_dwordx4 v130, s[24:25]
	s_waitcnt vmcnt(8)
	s_waitcnt lgkmcnt(0)
	s_barrier
	s_setprio 1
	v_mfma_f32_16x16x32_bf16 v[60:63], v[144:147], v[176:179], v[60:63]
	v_mfma_f32_16x16x32_bf16 v[56:59], v[152:155], v[176:179], v[56:59]
	v_mfma_f32_16x16x32_bf16 v[48:51], v[144:147], v[184:187], v[48:51]
	v_mfma_f32_16x16x32_bf16 v[40:43], v[152:155], v[184:187], v[40:43]
	v_mfma_f32_16x16x32_bf16 v[32:35], v[144:147], v[200:203], v[32:35]
	v_mfma_f32_16x16x32_bf16 v[24:27], v[152:155], v[200:203], v[24:27]
	v_mfma_f32_16x16x32_bf16 v[16:19], v[144:147], v[208:211], v[16:19]
	v_mfma_f32_16x16x32_bf16 v[8:11], v[152:155], v[208:211], v[8:11]
	v_mfma_f32_16x16x32_bf16 v[60:63], v[148:151], v[180:183], v[60:63]
	v_mfma_f32_16x16x32_bf16 v[56:59], v[156:159], v[180:183], v[56:59]
	v_mfma_f32_16x16x32_bf16 v[48:51], v[148:151], v[196:199], v[48:51]
	v_mfma_f32_16x16x32_bf16 v[40:43], v[156:159], v[196:199], v[40:43]
	v_mfma_f32_16x16x32_bf16 v[32:35], v[148:151], v[204:207], v[32:35]
	v_mfma_f32_16x16x32_bf16 v[24:27], v[156:159], v[204:207], v[24:27]
	v_mfma_f32_16x16x32_bf16 v[16:19], v[148:151], v[212:215], v[16:19]
	v_mfma_f32_16x16x32_bf16 v[8:11], v[156:159], v[212:215], v[8:11]
	v_mfma_f32_16x16x32_bf16 v[52:55], v[160:163], v[176:179], v[52:55]
	v_mfma_f32_16x16x32_bf16 v[44:47], v[168:171], v[176:179], v[44:47]
	v_mfma_f32_16x16x32_bf16 v[36:39], v[160:163], v[184:187], v[36:39]
	v_mfma_f32_16x16x32_bf16 v[28:31], v[168:171], v[184:187], v[28:31]
	v_mfma_f32_16x16x32_bf16 v[20:23], v[160:163], v[200:203], v[20:23]
	v_mfma_f32_16x16x32_bf16 v[12:15], v[168:171], v[200:203], v[12:15]
	v_mfma_f32_16x16x32_bf16 v[4:7], v[160:163], v[208:211], v[4:7]
	v_mfma_f32_16x16x32_bf16 v[0:3], v[168:171], v[208:211], v[0:3]
	v_mfma_f32_16x16x32_bf16 v[52:55], v[164:167], v[180:183], v[52:55]
	v_mfma_f32_16x16x32_bf16 v[44:47], v[172:175], v[180:183], v[44:47]
	v_mfma_f32_16x16x32_bf16 v[36:39], v[164:167], v[196:199], v[36:39]
	v_mfma_f32_16x16x32_bf16 v[28:31], v[172:175], v[196:199], v[28:31]
	v_mfma_f32_16x16x32_bf16 v[20:23], v[164:167], v[204:207], v[20:23]
	v_mfma_f32_16x16x32_bf16 v[12:15], v[172:175], v[204:207], v[12:15]
	v_mfma_f32_16x16x32_bf16 v[4:7], v[164:167], v[212:215], v[4:7]
	v_mfma_f32_16x16x32_bf16 v[0:3], v[172:175], v[212:215], v[0:3]
	s_setprio 0
	s_barrier
	s_add_u32 s22, s22, 0x400000
	s_addc_u32 s23, s23, 0
	s_add_u32 s42, s42, 0x40000
	s_addc_u32 s43, s43, 0
	s_cmp_gt_u32 s44, 61
	s_mov_b32 s44, s45
	s_cbranch_scc0 .LBB0_678
	v_lshl_or_b32 v142, s41, 8, v192
	v_lshl_add_u32 v144, s18, 8, v190
	v_ashrrev_i32_e32 v143, 31, v142
	v_ashrrev_i32_e32 v145, 31, v144
	v_lshl_add_u64 v[146:147], v[142:143], 1, s[12:13]
	v_lshlrev_b64 v[140:141], 11, v[144:145]
	v_lshl_add_u64 v[140:141], v[146:147], 0, v[140:141]
	global_load_dwordx2 v[196:197], v[140:141], off
	global_load_dwordx2 v[198:199], v[140:141], off offset:32
	global_load_dwordx2 v[200:201], v[140:141], off offset:256
	v_or_b32_e32 v202, 16, v144
	v_ashrrev_i32_e32 v203, 31, v202
	global_load_dwordx2 v[204:205], v[140:141], off offset:288
	v_lshlrev_b64 v[140:141], 11, v[202:203]
	v_lshl_add_u64 v[148:149], v[146:147], 0, v[140:141]
	global_load_dwordx2 v[206:207], v[148:149], off
	global_load_dwordx2 v[208:209], v[148:149], off offset:32
	global_load_dwordx2 v[210:211], v[148:149], off offset:256
	global_load_dwordx2 v[212:213], v[148:149], off offset:288
	v_or_b32_e32 v188, 32, v144
	v_or_b32_e32 v178, 48, v144
	v_add_u32_e32 v168, 0x80, v144
	v_add_u32_e32 v160, 0x90, v144
	v_add_u32_e32 v150, 0xa0, v144
	v_add_u32_e32 v140, 0xb0, v144
	v_ashrrev_i32_e32 v189, 31, v188
	v_ashrrev_i32_e32 v179, 31, v178
	v_ashrrev_i32_e32 v169, 31, v168
	v_ashrrev_i32_e32 v161, 31, v160
	v_ashrrev_i32_e32 v151, 31, v150
	v_ashrrev_i32_e32 v141, 31, v140
	v_lshlrev_b64 v[152:153], 12, v[144:145]
	v_lshlrev_b64 v[144:145], 2, v[142:143]
	v_lshlrev_b64 v[142:143], 11, v[188:189]
	v_lshlrev_b64 v[154:155], 11, v[178:179]
	v_lshlrev_b64 v[156:157], 11, v[168:169]
	v_lshlrev_b64 v[158:159], 11, v[160:161]
	v_lshlrev_b64 v[162:163], 11, v[150:151]
	v_lshlrev_b64 v[164:165], 11, v[140:141]
	v_lshl_add_u64 v[152:153], s[78:79], 0, v[152:153]
	v_lshl_add_u64 v[142:143], v[146:147], 0, v[142:143]
	v_lshl_add_u64 v[154:155], v[146:147], 0, v[154:155]
	v_lshl_add_u64 v[156:157], v[146:147], 0, v[156:157]
	v_lshl_add_u64 v[158:159], v[146:147], 0, v[158:159]
	v_lshl_add_u64 v[148:149], v[146:147], 0, v[162:163]
	v_lshl_add_u64 v[214:215], v[146:147], 0, v[164:165]
	v_lshl_add_u64 v[216:217], v[152:153], 0, v[144:145]
	global_load_dwordx2 v[218:219], v[142:143], off
	global_load_dwordx2 v[220:221], v[142:143], off offset:32
	global_load_dwordx2 v[222:223], v[142:143], off offset:256
	global_load_dwordx2 v[224:225], v[142:143], off offset:288
	global_load_dwordx2 v[226:227], v[154:155], off
	global_load_dwordx2 v[228:229], v[154:155], off offset:32
	global_load_dwordx2 v[186:187], v[154:155], off offset:256
	global_load_dwordx2 v[184:185], v[154:155], off offset:288
	global_load_dwordx2 v[182:183], v[156:157], off
	global_load_dwordx2 v[180:181], v[156:157], off offset:32
	global_load_dwordx2 v[176:177], v[156:157], off offset:256
	global_load_dwordx2 v[174:175], v[156:157], off offset:288
	global_load_dwordx2 v[172:173], v[158:159], off
	global_load_dwordx2 v[170:171], v[158:159], off offset:32
	global_load_dwordx2 v[166:167], v[158:159], off offset:256
	global_load_dwordx2 v[164:165], v[158:159], off offset:288
	global_load_dwordx2 v[162:163], v[148:149], off
	s_nop 0
	global_load_dwordx2 v[158:159], v[148:149], off offset:32
	global_load_dwordx2 v[156:157], v[148:149], off offset:256
	global_load_dwordx2 v[154:155], v[148:149], off offset:288
	global_load_dwordx2 v[152:153], v[214:215], off
	s_nop 0
	global_load_dwordx2 v[148:149], v[214:215], off offset:32
	global_load_dwordx2 v[146:147], v[214:215], off offset:256
	global_load_dwordx2 v[142:143], v[214:215], off offset:288
	s_and_b64 vcc, exec, s[0:1]
	s_mov_b32 s41, s8
	s_mov_b32 s18, s10
	s_mov_b64 s[22:23], s[16:17]
	s_mov_b64 s[20:21], s[14:15]
	s_waitcnt vmcnt(0)
	v_lshlrev_b32_e32 v214, 16, v196
	v_and_b32_e32 v215, 0xffff0000, v196
	v_lshlrev_b32_e32 v196, 16, v197
	v_and_b32_e32 v197, 0xffff0000, v197
	v_lshlrev_b32_e32 v230, 16, v198
	v_and_b32_e32 v231, 0xffff0000, v198
	v_lshlrev_b32_e32 v198, 16, v199
	v_and_b32_e32 v199, 0xffff0000, v199
	v_pk_add_f32 v[126:127], v[126:127], v[196:197]
	v_pk_add_f32 v[124:125], v[124:125], v[214:215]
	v_pk_add_f32 v[120:121], v[120:121], v[230:231]
	v_lshlrev_b32_e32 v232, 16, v200
	v_and_b32_e32 v233, 0xffff0000, v200
	v_pk_add_f32 v[122:123], v[122:123], v[198:199]
	global_store_dwordx4 v[216:217], v[124:127], off
	global_store_dwordx4 v[216:217], v[120:123], off offset:64
	v_pk_add_f32 v[116:117], v[116:117], v[232:233]
	s_nop 0
	v_lshlrev_b32_e32 v120, 16, v201
	v_and_b32_e32 v121, 0xffff0000, v201
	v_pk_add_f32 v[118:119], v[118:119], v[120:121]
	global_store_dwordx4 v[216:217], v[116:119], off offset:512
	s_nop 1
	v_lshlrev_b32_e32 v116, 16, v204
	v_and_b32_e32 v117, 0xffff0000, v204
	v_lshlrev_b32_e32 v118, 16, v205
	v_and_b32_e32 v119, 0xffff0000, v205
	v_pk_add_f32 v[110:111], v[110:111], v[118:119]
	v_pk_add_f32 v[108:109], v[108:109], v[116:117]
	global_store_dwordx4 v[216:217], v[108:111], off offset:576
	v_lshlrev_b64 v[116:117], 12, v[202:203]
	s_nop 0
	v_lshlrev_b32_e32 v108, 16, v206
	v_and_b32_e32 v109, 0xffff0000, v206
	v_lshlrev_b32_e32 v110, 16, v207
	v_and_b32_e32 v111, 0xffff0000, v207
	v_pk_add_f32 v[108:109], v[112:113], v[108:109]
	v_lshl_add_u64 v[112:113], s[78:79], 0, v[116:117]
	v_pk_add_f32 v[110:111], v[114:115], v[110:111]
	v_lshl_add_u64 v[112:113], v[112:113], 0, v[144:145]
	global_store_dwordx4 v[112:113], v[108:111], off
	s_nop 1
	v_lshlrev_b32_e32 v108, 16, v208
	v_and_b32_e32 v109, 0xffff0000, v208
	v_lshlrev_b32_e32 v110, 16, v209
	v_and_b32_e32 v111, 0xffff0000, v209
	v_pk_add_f32 v[106:107], v[106:107], v[110:111]
	v_pk_add_f32 v[104:105], v[104:105], v[108:109]
	global_store_dwordx4 v[112:113], v[104:107], off offset:64
	s_nop 1
	v_lshlrev_b32_e32 v104, 16, v210
	v_and_b32_e32 v105, 0xffff0000, v210
	v_lshlrev_b32_e32 v106, 16, v211
	v_and_b32_e32 v107, 0xffff0000, v211
	v_pk_add_f32 v[102:103], v[102:103], v[106:107]
	v_pk_add_f32 v[100:101], v[100:101], v[104:105]
	global_store_dwordx4 v[112:113], v[100:103], off offset:512
	s_nop 1
	v_lshlrev_b32_e32 v100, 16, v212
	v_and_b32_e32 v101, 0xffff0000, v212
	v_lshlrev_b32_e32 v102, 16, v213
	v_and_b32_e32 v103, 0xffff0000, v213
	v_pk_add_f32 v[94:95], v[94:95], v[102:103]
	v_pk_add_f32 v[92:93], v[92:93], v[100:101]
	global_store_dwordx4 v[112:113], v[92:95], off offset:576
	v_lshlrev_b64 v[100:101], 12, v[188:189]
	s_nop 0
	v_lshlrev_b32_e32 v92, 16, v218
	v_and_b32_e32 v93, 0xffff0000, v218
	v_lshlrev_b32_e32 v94, 16, v219
	v_and_b32_e32 v95, 0xffff0000, v219
	v_pk_add_f32 v[92:93], v[96:97], v[92:93]
	v_lshl_add_u64 v[96:97], s[78:79], 0, v[100:101]
	v_pk_add_f32 v[94:95], v[98:99], v[94:95]
	v_lshl_add_u64 v[96:97], v[96:97], 0, v[144:145]
	global_store_dwordx4 v[96:97], v[92:95], off
	s_nop 1
	v_lshlrev_b32_e32 v92, 16, v220
	v_and_b32_e32 v93, 0xffff0000, v220
	v_lshlrev_b32_e32 v94, 16, v221
	v_and_b32_e32 v95, 0xffff0000, v221
	v_pk_add_f32 v[90:91], v[90:91], v[94:95]
	v_pk_add_f32 v[88:89], v[88:89], v[92:93]
	global_store_dwordx4 v[96:97], v[88:91], off offset:64
	s_nop 1
	v_lshlrev_b32_e32 v88, 16, v222
	v_and_b32_e32 v89, 0xffff0000, v222
	v_lshlrev_b32_e32 v90, 16, v223
	v_and_b32_e32 v91, 0xffff0000, v223
	v_pk_add_f32 v[86:87], v[86:87], v[90:91]
	v_pk_add_f32 v[84:85], v[84:85], v[88:89]
	global_store_dwordx4 v[96:97], v[84:87], off offset:512
	s_nop 1
	v_lshlrev_b32_e32 v84, 16, v224
	v_and_b32_e32 v85, 0xffff0000, v224
	v_lshlrev_b32_e32 v86, 16, v225
	v_and_b32_e32 v87, 0xffff0000, v225
	v_pk_add_f32 v[78:79], v[78:79], v[86:87]
	v_pk_add_f32 v[76:77], v[76:77], v[84:85]
	global_store_dwordx4 v[96:97], v[76:79], off offset:576
	v_lshlrev_b64 v[84:85], 12, v[178:179]
	s_nop 0
	v_lshlrev_b32_e32 v76, 16, v226
	v_and_b32_e32 v77, 0xffff0000, v226
	v_lshlrev_b32_e32 v78, 16, v227
	v_and_b32_e32 v79, 0xffff0000, v227
	v_pk_add_f32 v[76:77], v[80:81], v[76:77]
	v_lshl_add_u64 v[80:81], s[78:79], 0, v[84:85]
	v_pk_add_f32 v[78:79], v[82:83], v[78:79]
	v_lshl_add_u64 v[80:81], v[80:81], 0, v[144:145]
	global_store_dwordx4 v[80:81], v[76:79], off
	s_nop 1
	v_lshlrev_b32_e32 v76, 16, v228
	v_and_b32_e32 v77, 0xffff0000, v228
	v_lshlrev_b32_e32 v78, 16, v229
	v_and_b32_e32 v79, 0xffff0000, v229
	v_pk_add_f32 v[74:75], v[74:75], v[78:79]
	v_pk_add_f32 v[72:73], v[72:73], v[76:77]
	global_store_dwordx4 v[80:81], v[72:75], off offset:64
	s_nop 1
	v_lshlrev_b32_e32 v72, 16, v186
	v_and_b32_e32 v73, 0xffff0000, v186
	v_lshlrev_b32_e32 v74, 16, v187
	v_and_b32_e32 v75, 0xffff0000, v187
	v_pk_add_f32 v[70:71], v[70:71], v[74:75]
	v_pk_add_f32 v[68:69], v[68:69], v[72:73]
	global_store_dwordx4 v[80:81], v[68:71], off offset:512
	s_nop 1
	v_lshlrev_b32_e32 v68, 16, v184
	v_and_b32_e32 v69, 0xffff0000, v184
	v_lshlrev_b32_e32 v70, 16, v185
	v_and_b32_e32 v71, 0xffff0000, v185
	v_pk_add_f32 v[66:67], v[66:67], v[70:71]
	v_pk_add_f32 v[64:65], v[64:65], v[68:69]
	global_store_dwordx4 v[80:81], v[64:67], off offset:576
	v_lshlrev_b32_e32 v68, 16, v183
	v_and_b32_e32 v69, 0xffff0000, v183
	v_lshlrev_b64 v[64:65], 12, v[168:169]
	v_lshlrev_b32_e32 v66, 16, v182
	v_and_b32_e32 v67, 0xffff0000, v182
	v_lshl_add_u64 v[64:65], s[78:79], 0, v[64:65]
	v_pk_add_f32 v[62:63], v[62:63], v[68:69]
	v_pk_add_f32 v[60:61], v[60:61], v[66:67]
	v_lshl_add_u64 v[64:65], v[64:65], 0, v[144:145]
	global_store_dwordx4 v[64:65], v[60:63], off
	s_nop 1
	v_lshlrev_b32_e32 v60, 16, v180
	v_and_b32_e32 v61, 0xffff0000, v180
	v_lshlrev_b32_e32 v62, 16, v181
	v_and_b32_e32 v63, 0xffff0000, v181
	v_pk_add_f32 v[58:59], v[58:59], v[62:63]
	v_pk_add_f32 v[56:57], v[56:57], v[60:61]
	global_store_dwordx4 v[64:65], v[56:59], off offset:64
	s_nop 1
	v_lshlrev_b32_e32 v56, 16, v176
	v_and_b32_e32 v57, 0xffff0000, v176
	v_lshlrev_b32_e32 v58, 16, v177
	v_and_b32_e32 v59, 0xffff0000, v177
	v_pk_add_f32 v[54:55], v[54:55], v[58:59]
	v_pk_add_f32 v[52:53], v[52:53], v[56:57]
	global_store_dwordx4 v[64:65], v[52:55], off offset:512
	s_nop 1
	v_lshlrev_b32_e32 v52, 16, v174
	v_and_b32_e32 v53, 0xffff0000, v174
	v_lshlrev_b32_e32 v54, 16, v175
	v_and_b32_e32 v55, 0xffff0000, v175
	v_pk_add_f32 v[46:47], v[46:47], v[54:55]
	v_pk_add_f32 v[44:45], v[44:45], v[52:53]
	global_store_dwordx4 v[64:65], v[44:47], off offset:576
	v_lshlrev_b64 v[52:53], 12, v[160:161]
	s_nop 0
	v_lshlrev_b32_e32 v44, 16, v172
	v_and_b32_e32 v45, 0xffff0000, v172
	v_lshlrev_b32_e32 v46, 16, v173
	v_and_b32_e32 v47, 0xffff0000, v173
	v_pk_add_f32 v[44:45], v[48:49], v[44:45]
	v_lshl_add_u64 v[48:49], s[78:79], 0, v[52:53]
	v_pk_add_f32 v[46:47], v[50:51], v[46:47]
	v_lshl_add_u64 v[48:49], v[48:49], 0, v[144:145]
	global_store_dwordx4 v[48:49], v[44:47], off
	s_nop 1
	v_lshlrev_b32_e32 v44, 16, v170
	v_and_b32_e32 v45, 0xffff0000, v170
	v_lshlrev_b32_e32 v46, 16, v171
	v_and_b32_e32 v47, 0xffff0000, v171
	v_pk_add_f32 v[42:43], v[42:43], v[46:47]
	v_pk_add_f32 v[40:41], v[40:41], v[44:45]
	global_store_dwordx4 v[48:49], v[40:43], off offset:64
	s_nop 1
	v_lshlrev_b32_e32 v40, 16, v166
	v_and_b32_e32 v41, 0xffff0000, v166
	v_lshlrev_b32_e32 v42, 16, v167
	v_and_b32_e32 v43, 0xffff0000, v167
	v_pk_add_f32 v[38:39], v[38:39], v[42:43]
	v_pk_add_f32 v[36:37], v[36:37], v[40:41]
	global_store_dwordx4 v[48:49], v[36:39], off offset:512
	s_nop 1
	v_lshlrev_b32_e32 v36, 16, v164
	v_and_b32_e32 v37, 0xffff0000, v164
	v_lshlrev_b32_e32 v38, 16, v165
	v_and_b32_e32 v39, 0xffff0000, v165
	v_pk_add_f32 v[30:31], v[30:31], v[38:39]
	v_pk_add_f32 v[28:29], v[28:29], v[36:37]
	global_store_dwordx4 v[48:49], v[28:31], off offset:576
	v_lshlrev_b64 v[36:37], 12, v[150:151]
	s_nop 0
	v_lshlrev_b32_e32 v28, 16, v162
	v_and_b32_e32 v29, 0xffff0000, v162
	v_lshlrev_b32_e32 v30, 16, v163
	v_and_b32_e32 v31, 0xffff0000, v163
	v_pk_add_f32 v[28:29], v[32:33], v[28:29]
	v_lshl_add_u64 v[32:33], s[78:79], 0, v[36:37]
	v_pk_add_f32 v[30:31], v[34:35], v[30:31]
	v_lshl_add_u64 v[32:33], v[32:33], 0, v[144:145]
	global_store_dwordx4 v[32:33], v[28:31], off
	s_nop 1
	v_lshlrev_b32_e32 v28, 16, v158
	v_and_b32_e32 v29, 0xffff0000, v158
	v_lshlrev_b32_e32 v30, 16, v159
	v_and_b32_e32 v31, 0xffff0000, v159
	v_pk_add_f32 v[26:27], v[26:27], v[30:31]
	v_pk_add_f32 v[24:25], v[24:25], v[28:29]
	global_store_dwordx4 v[32:33], v[24:27], off offset:64
	s_nop 1
	v_lshlrev_b32_e32 v24, 16, v156
	v_and_b32_e32 v25, 0xffff0000, v156
	v_lshlrev_b32_e32 v26, 16, v157
	v_and_b32_e32 v27, 0xffff0000, v157
	v_pk_add_f32 v[22:23], v[22:23], v[26:27]
	v_pk_add_f32 v[20:21], v[20:21], v[24:25]
	global_store_dwordx4 v[32:33], v[20:23], off offset:512
	s_nop 1
	v_lshlrev_b32_e32 v20, 16, v154
	v_and_b32_e32 v21, 0xffff0000, v154
	v_lshlrev_b32_e32 v22, 16, v155
	v_and_b32_e32 v23, 0xffff0000, v155
	v_pk_add_f32 v[14:15], v[14:15], v[22:23]
	v_pk_add_f32 v[12:13], v[12:13], v[20:21]
	global_store_dwordx4 v[32:33], v[12:15], off offset:576
	v_lshlrev_b64 v[20:21], 12, v[140:141]
	s_nop 0
	v_lshlrev_b32_e32 v12, 16, v152
	v_and_b32_e32 v13, 0xffff0000, v152
	v_lshlrev_b32_e32 v14, 16, v153
	v_and_b32_e32 v15, 0xffff0000, v153
	v_pk_add_f32 v[12:13], v[16:17], v[12:13]
	v_lshl_add_u64 v[16:17], s[78:79], 0, v[20:21]
	v_pk_add_f32 v[14:15], v[18:19], v[14:15]
	v_lshl_add_u64 v[16:17], v[16:17], 0, v[144:145]
	global_store_dwordx4 v[16:17], v[12:15], off
	s_nop 1
	v_lshlrev_b32_e32 v12, 16, v148
	v_and_b32_e32 v13, 0xffff0000, v148
	v_lshlrev_b32_e32 v14, 16, v149
	v_and_b32_e32 v15, 0xffff0000, v149
	v_pk_add_f32 v[10:11], v[10:11], v[14:15]
	v_pk_add_f32 v[8:9], v[8:9], v[12:13]
	global_store_dwordx4 v[16:17], v[8:11], off offset:64
	s_nop 1
	v_lshlrev_b32_e32 v8, 16, v146
	v_and_b32_e32 v9, 0xffff0000, v146
	v_lshlrev_b32_e32 v10, 16, v147
	v_and_b32_e32 v11, 0xffff0000, v147
	v_pk_add_f32 v[6:7], v[6:7], v[10:11]
	v_pk_add_f32 v[4:5], v[4:5], v[8:9]
	global_store_dwordx4 v[16:17], v[4:7], off offset:512
	s_nop 1
	v_lshlrev_b32_e32 v4, 16, v142
	v_and_b32_e32 v5, 0xffff0000, v142
	v_lshlrev_b32_e32 v6, 16, v143
	v_and_b32_e32 v7, 0xffff0000, v143
	v_pk_add_f32 v[2:3], v[2:3], v[6:7]
	v_pk_add_f32 v[0:1], v[0:1], v[4:5]
	global_store_dwordx4 v[16:17], v[0:3], off offset:576
	s_cbranch_vccz .LBB0_671
	s_waitcnt vmcnt(0)
	s_cmpk_gt_u32 s28, 0xff
	s_cbranch_scc1 .LBB0_682
	s_barrier
